# P4 attention loops: counted vmcnt waits so next-tile K/V prefetch stays in flight (was drained by conservative vmcnt)
# baseline (speedup 1.0000x reference)
; #define LAS __attribute__((address_space(3)))
; __device__ __forceinline__ void k_frag(bf16x8 (&kq)[4], LAS unsigned char* kl, const bf16x8 (&kr)[4], int lane) {
; #pragma unroll
;     for (int i = 0; i < 4; ++i) { const int id = lane + 64 * i; *(LAS bf16x8*)(kl + (id >> 3) * VL_PITCH + (id & 7) * 16) = kr[i]; }
;     const int r = lane & 31, hh = lane >> 5;
; #pragma unroll
;     for (int s = 0; s < 4; ++s) kq[s] = *(const LAS bf16x8*)(kl + r * VL_PITCH + 32 * s + 16 * hh);
; }
; __device__ __forceinline__ void v_stage_store(LAS unsigned char* vl, const u32x4 (&vr)[4], int lane) {
; #pragma unroll
;     for (int i = 0; i < 4; ++i) { const int id = lane + 64 * i; *(LAS u32x4*)(vl + (id >> 3) * VL_PITCH + (id & 7) * 16) = vr[i]; }
; }
.LBB0_763:
	s_waitcnt vmcnt(15)
	ds_write_b128 v131, v[50:53] offset:4608
	s_waitcnt vmcnt(13)
	ds_write_b128 v131, v[58:61] offset:5760
	s_waitcnt vmcnt(11)
	ds_write_b128 v131, v[66:69] offset:6912
	s_waitcnt vmcnt(9)
	ds_write_b128 v131, v[86:89] offset:8064
	ds_read_b128 v[34:37], v133 offset:4608
	ds_read_b128 v[142:145], v133 offset:4640
	s_cmp_eq_u32 s16, s67
	s_cselect_b64 vcc, -1, 0
	s_waitcnt lgkmcnt(1)
	v_mfma_f32_32x32x16_bf16 v[34:49], v[34:37], v[110:113], 0
	s_waitcnt lgkmcnt(0)
	v_mfma_f32_32x32x16_bf16 v[34:49], v[142:145], v[118:121], v[34:49]
	ds_read_b128 v[142:145], v133 offset:4672
	ds_read_b128 v[190:193], v133 offset:4704
	ds_write_b128 v131, v[54:57]
	ds_write_b128 v131, v[62:65] offset:1152
	ds_write_b128 v131, v[70:73] offset:2304
	s_waitcnt vmcnt(8)
	ds_write_b128 v131, v[94:97] offset:3456
	s_waitcnt lgkmcnt(5)
	v_mfma_f32_32x32x16_bf16 v[34:49], v[142:145], v[122:125], v[34:49]
	v_cndmask_b32_e32 v142, 64, v1, vcc
	v_cmp_lt_u32_e32 vcc, v177, v142
	v_cmp_lt_u32_e64 s[4:5], v199, v142
	v_cmp_lt_u32_e64 s[6:7], v200, v142
	s_waitcnt lgkmcnt(4)
	v_mfma_f32_32x32x16_bf16 v[34:49], v[190:193], v[126:129], v[34:49]
	s_nop 11
	v_max_f32_e32 v34, v34, v34
	v_max_f32_e32 v35, v35, v35
	v_max_f32_e32 v36, v36, v36
	v_min_f32_e32 v34, 0x42fc0000, v34
	v_max_f32_e32 v37, v37, v37
	v_min_f32_e32 v35, 0x42fc0000, v35
	v_min_f32_e32 v36, 0x42fc0000, v36
	v_exp_f32_e32 v34, v34
	v_min_f32_e32 v37, 0x42fc0000, v37
	v_exp_f32_e32 v35, v35
	v_exp_f32_e32 v36, v36
	v_exp_f32_e32 v37, v37
	v_add_f32_e32 v143, 1.0, v34
	v_max_f32_e32 v38, v38, v38
	v_add_f32_e32 v144, 1.0, v35
	v_add_f32_e32 v145, 1.0, v36
	v_rcp_f32_e32 v143, v143
	v_min_f32_e32 v38, 0x42fc0000, v38
	v_add_f32_e32 v148, 1.0, v37
	v_rcp_f32_e32 v144, v144
	v_rcp_f32_e32 v145, v145
	v_exp_f32_e32 v38, v38
	v_rcp_f32_e32 v148, v148
	v_max_f32_e32 v39, v39, v39
	v_min_f32_e32 v39, 0x42fc0000, v39
	v_mul_f32_e32 v34, v34, v143
	v_exp_f32_e32 v39, v39
	v_cndmask_b32_e32 v181, 1.0, v143, vcc
	v_cndmask_b32_e64 v143, 1.0, v144, s[4:5]
	v_mul_f32_e32 v35, v35, v144
	v_cndmask_b32_e64 v144, 1.0, v145, s[6:7]
	v_mul_f32_e32 v36, v36, v145
	v_cndmask_b32_e32 v145, 0, v34, vcc
	v_cmp_lt_u32_e32 vcc, v201, v142
	v_cndmask_b32_e64 v34, 0, v35, s[4:5]
	v_mul_f32_e32 v35, v181, v143
	v_cndmask_b32_e32 v181, 1.0, v148, vcc
	v_mul_f32_e32 v37, v37, v148
	v_add_f32_e32 v148, 1.0, v38
	v_rcp_f32_e32 v148, v148
	v_max_f32_e32 v40, v40, v40
	v_add_f32_e32 v185, 1.0, v39
	v_min_f32_e32 v40, 0x42fc0000, v40
	v_rcp_f32_e32 v185, v185
	v_exp_f32_e32 v40, v40
	v_mul_f32_e32 v35, v144, v35
	v_cndmask_b32_e32 v37, 0, v37, vcc
	v_cmp_lt_u32_e32 vcc, v202, v142
	v_mul_f32_e32 v38, v38, v148
	v_mul_f32_e32 v183, v181, v35
	v_cndmask_b32_e32 v35, 1.0, v148, vcc
	v_cndmask_b32_e32 v38, 0, v38, vcc
	v_cmp_lt_u32_e32 vcc, v203, v142
	v_max_f32_e32 v41, v41, v41
	v_mul_f32_e32 v39, v39, v185
	v_cndmask_b32_e32 v148, 1.0, v185, vcc
	v_add_f32_e32 v185, 1.0, v40
	v_min_f32_e32 v41, 0x42fc0000, v41
	v_rcp_f32_e32 v185, v185
	v_exp_f32_e32 v41, v41
	v_cndmask_b32_e32 v39, 0, v39, vcc
	v_cmp_lt_u32_e32 vcc, v204, v142
	v_max_f32_e32 v42, v42, v42
	v_mul_f32_e32 v40, v40, v185
	v_cndmask_b32_e32 v187, 1.0, v185, vcc
	v_add_f32_e32 v185, 1.0, v41
	v_min_f32_e32 v42, 0x42fc0000, v42
	v_rcp_f32_e32 v185, v185
	v_exp_f32_e32 v42, v42
	v_cndmask_b32_e32 v40, 0, v40, vcc
	v_cmp_lt_u32_e32 vcc, v205, v142
	v_mul_f32_e32 v41, v41, v185
	v_max_f32_e32 v43, v43, v43
	v_cndmask_b32_e32 v189, 1.0, v185, vcc
	v_add_f32_e32 v185, 1.0, v42
	v_rcp_f32_e32 v185, v185
	v_min_f32_e32 v43, 0x42fc0000, v43
	v_exp_f32_e32 v43, v43
	v_cndmask_b32_e32 v41, 0, v41, vcc
	v_cmp_lt_u32_e32 vcc, v206, v142
	v_mul_f32_e32 v42, v42, v185
	v_max_f32_e32 v44, v44, v44
	v_cndmask_b32_e32 v190, 1.0, v185, vcc
	v_cndmask_b32_e32 v185, 0, v42, vcc
	v_add_f32_e32 v42, 1.0, v43
	v_min_f32_e32 v44, 0x42fc0000, v44
	v_rcp_f32_e32 v42, v42
	v_exp_f32_e32 v44, v44
	v_cmp_lt_u32_e32 vcc, v207, v142
	v_max_f32_e32 v45, v45, v45
	v_min_f32_e32 v45, 0x42fc0000, v45
	v_cndmask_b32_e32 v191, 1.0, v42, vcc
	v_mul_f32_e32 v42, v43, v42
	v_add_f32_e32 v43, 1.0, v44
	v_rcp_f32_e32 v43, v43
	v_exp_f32_e32 v45, v45
	v_cndmask_b32_e32 v192, 0, v42, vcc
	v_cmp_lt_u32_e32 vcc, v208, v142
	v_mul_f32_e32 v42, v190, v191
	v_max_f32_e32 v47, v47, v47
	v_cndmask_b32_e32 v190, 1.0, v43, vcc
	v_mul_f32_e32 v43, v44, v43
	v_max_f32_e32 v44, v46, v46
	v_cndmask_b32_e32 v193, 0, v43, vcc
	v_add_f32_e32 v43, 1.0, v45
	v_min_f32_e32 v44, 0x42fc0000, v44
	v_rcp_f32_e32 v43, v43
	v_exp_f32_e32 v44, v44
	v_min_f32_e32 v47, 0x42fc0000, v47
	v_exp_f32_e32 v47, v47
	v_cmp_lt_u32_e32 vcc, v209, v142
	v_max_f32_e32 v48, v48, v48
	v_min_f32_e32 v48, 0x42fc0000, v48
	v_cndmask_b32_e32 v46, 1.0, v43, vcc
	v_mul_f32_e32 v43, v45, v43
	v_add_f32_e32 v45, 1.0, v44
	v_rcp_f32_e32 v45, v45
	v_add_f32_e32 v195, 1.0, v47
	v_rcp_f32_e32 v195, v195
	v_exp_f32_e32 v48, v48
	v_cndmask_b32_e32 v43, 0, v43, vcc
	v_cmp_lt_u32_e32 vcc, v210, v142
	v_mul_f32_e32 v44, v44, v45
	v_max_f32_e32 v49, v49, v49
	v_cndmask_b32_e32 v194, 1.0, v45, vcc
	v_cndmask_b32_e32 v44, 0, v44, vcc
	v_cmp_lt_u32_e32 vcc, v211, v142
	v_mul_f32_e32 v47, v47, v195
	v_min_f32_e32 v49, 0x42fc0000, v49
	v_cndmask_b32_e32 v45, 1.0, v195, vcc
	v_add_f32_e32 v195, 1.0, v48
	v_rcp_f32_e32 v195, v195
	v_exp_f32_e32 v49, v49
	v_cndmask_b32_e32 v47, 0, v47, vcc
	v_cmp_lt_u32_e32 vcc, v212, v142
	v_mul_f32_e32 v48, v48, v195
	v_mul_f32_e32 v194, v194, v45
	v_cndmask_b32_e32 v218, 1.0, v195, vcc
	v_add_f32_e32 v195, 1.0, v49
	v_rcp_f32_e32 v195, v195
	v_cndmask_b32_e32 v48, 0, v48, vcc
	v_cmp_lt_u32_e32 vcc, v213, v142
	v_mul_f32_e32 v194, v218, v194
	v_mul_f32_e32 v49, v49, v195
	v_cndmask_b32_e32 v142, 1.0, v195, vcc
	v_mul_f32_e32 v194, v142, v194
	ds_bpermute_b32 v195, v135, v194
	v_mul_f32_e32 v42, v190, v42
	v_mul_f32_e32 v35, v35, v148
	v_mul_f32_e32 v42, v46, v42
	v_mul_f32_e32 v35, v187, v35
	s_waitcnt lgkmcnt(0)
; #define LAS __attribute__((address_space(3)))
; __device__ __forceinline__ unsigned cvtpk(float lo, float hi) { f32x2 v = {lo, hi}; bf2_t b = __builtin_convertvector(v, bf2_t); return __builtin_bit_cast(unsigned, b); }
; #define SB_LD(KF, VR, KK) do { _Pragma("unroll") for (int i = 0; i < 4; ++i) { const int id = lane + 64 * i; KF[i] = *(const bf16x8*)(kcol + (size_t)((KK) + (id >> 3)) * QKVW + (id & 7) * 8); VR[i] = *(const u32x4*)(vcol + (size_t)((KK) + (id >> 3)) * QKVW + (id & 7) * 8); } } while (0)
; __device__ __forceinline__ void pv32(f32x16 (&o)[2], LAS unsigned char* vl, const f32x16& p, int lane) {
;     bf16x8 pf[2];
; #pragma unroll
;     for (int s = 0; s < 2; ++s) { u32x4 w; w.x = cvtpk(p[8 * s], p[8 * s + 1]); w.y = cvtpk(p[8 * s + 2], p[8 * s + 3]); w.z = cvtpk(p[8 * s + 4], p[8 * s + 5]); w.w = cvtpk(p[8 * s + 6], p[8 * s + 7]); pf[s] = __builtin_bit_cast(bf16x8, w); }
;     const int i = lane & 15, gidx = lane >> 4, hh = gidx >> 1;
;     LAS unsigned char* base = vl + (4 * hh + (i >> 2)) * VL_PITCH + (16 * (gidx & 1) + 4 * (i & 3)) * 2;
; #pragma unroll
;     for (int s = 0; s < 2; ++s)
; #pragma unroll
;         for (int dh = 0; dh < 2; ++dh) {
;             const v4i16_t lo = __builtin_amdgcn_ds_read_tr16_b64_v4i16((LAS v4i16_t*)(base + (16 * s) * VL_PITCH + 64 * dh));
;             const v4i16_t hi = __builtin_amdgcn_ds_read_tr16_b64_v4i16((LAS v4i16_t*)(base + (16 * s + 8) * VL_PITCH + 64 * dh));
;             const bf16x8 vf = (bf16x8){lo[0], lo[1], lo[2], lo[3], hi[0], hi[1], hi[2], hi[3]};
;             o[dh] = __builtin_amdgcn_mfma_f32_32x32x16_bf16(vf, pf[s], o[dh], 0, 0, 0);
;         }
; }
; __device__ __forceinline__ void sb_item(bf16_t* qkv, LAS unsigned char* vl, int h, int qb, int lane, bool dry) {
;     ...
;     bf16x8 kfA[4], kfB[4]; u32x4 vrA[4], vrB[4];
;     int k0 = t0;
;     SB_LD(kfA, vrA, k0);
;     for (;;) {
;         const bool m1 = k0 - 32 >= 0; if (m1) SB_LD(kfB, vrB, k0 - 32);
;         SB_TILE(kfA, vrA, k0);
;         if (!m1 || __all(carry < 1e-38f)) break;
;         const bool m2 = k0 - 64 >= 0; if (m2) SB_LD(kfA, vrA, k0 - 64);
;         SB_TILE(kfB, vrB, k0 - 32);
;         if (!m2 || __all(carry < 1e-38f)) break;
	v_cndmask_b32_e64 v222, 1.0, v195, s[2:3]
	ds_bpermute_b32 v221, v135, v42
	v_mul_f32_e32 v222, v137, v222
	v_mul_f32_e32 v35, v189, v35
	v_mul_f32_e32 v142, v142, v222
	ds_bpermute_b32 v220, v135, v35
	v_mul_f32_e32 v48, v48, v142
	v_mul_f32_e32 v142, v218, v142
	v_mul_f32_e32 v45, v45, v142
	v_mul_f32_e32 v218, v44, v45
	v_mul_f32_e32 v44, v194, v195
	v_mul_f32_e32 v44, v137, v44
	s_waitcnt lgkmcnt(1)
	v_cndmask_b32_e64 v45, 1.0, v221, s[2:3]
	ds_bpermute_b32 v219, v135, v183
	v_mul_f32_e32 v137, v45, v44
	v_mul_f32_e32 v42, v42, v221
	v_mul_f32_e32 v194, v43, v137
	v_mul_f32_e32 v42, v42, v44
	s_waitcnt lgkmcnt(1)
	v_cndmask_b32_e64 v43, 1.0, v220, s[2:3]
	v_mul_f32_e32 v43, v43, v42
	v_mul_f32_e32 v41, v41, v43
	v_mul_f32_e32 v43, v189, v43
	v_mul_f32_e32 v44, v40, v43
	v_mul_f32_e32 v40, v187, v43
	v_mul_f32_e32 v35, v35, v220
	v_mul_f32_e32 v43, v39, v40
	v_mul_f32_e32 v39, v148, v40
	v_mul_f32_e32 v148, v35, v42
	s_waitcnt lgkmcnt(0)
	v_cndmask_b32_e64 v35, 1.0, v219, s[2:3]
	v_mul_f32_e32 v35, v35, v148
	v_mul_f32_e32 v40, v38, v39
	v_mul_f32_e32 v39, v37, v35
	v_mul_f32_e32 v35, v181, v35
	v_mul_f32_e32 v38, v144, v35
	v_cndmask_b32_e64 v36, 0, v36, s[6:7]
	v_mul_f32_e32 v45, v34, v38
	v_mul_f32_e32 v38, v143, v38
	v_mul_f32_e32 v47, v47, v142
	v_mul_f32_e32 v42, v36, v35
	v_add_u32_e32 v142, v196, v197
	v_mul_f32_e32 v38, v145, v38
	ds_read_b64_tr_b16 v[34:35], v142
	ds_read_b64_tr_b16 v[36:37], v142 offset:1152
	v_cvt_pk_bf16_f32 v38, v38, v45
	v_cvt_pk_bf16_f32 v39, v42, v39
	v_cvt_pk_bf16_f32 v40, v40, v43
	v_cvt_pk_bf16_f32 v41, v44, v41
	ds_read_b64_tr_b16 v[44:45], v142 offset:1216
	ds_read_b64_tr_b16 v[42:43], v142 offset:64
	s_waitcnt lgkmcnt(2)
	v_mfma_f32_32x32x16_bf16 v[18:33], v[34:37], v[38:41], v[18:33]
	v_mul_f32_e32 v34, v46, v137
	v_mul_f32_e32 v46, v193, v34
	v_mul_f32_e32 v34, v190, v34
	v_mul_f32_e32 v137, v192, v34
	v_mul_f32_e32 v143, v191, v34
	ds_read_b64_tr_b16 v[34:35], v142 offset:2304
	ds_read_b64_tr_b16 v[36:37], v142 offset:3456
	v_cndmask_b32_e32 v49, 0, v49, vcc
	s_waitcnt lgkmcnt(2)
	v_mfma_f32_32x32x16_bf16 v[2:17], v[42:45], v[38:41], v[2:17]
	ds_read_b64_tr_b16 v[44:45], v142 offset:3520
	ds_read_b64_tr_b16 v[42:43], v142 offset:2368
	v_mul_f32_e32 v49, v49, v222
	v_mul_f32_e32 v38, v185, v143
	v_cvt_pk_bf16_f32 v38, v38, v137
	v_cvt_pk_bf16_f32 v39, v46, v194
	v_cvt_pk_bf16_f32 v40, v218, v47
	v_cvt_pk_bf16_f32 v41, v48, v49
	s_andn2_b64 vcc, exec, s[40:41]
	s_mov_b64 s[4:5], 0
	s_waitcnt lgkmcnt(2)
	v_mfma_f32_32x32x16_bf16 v[18:33], v[34:37], v[38:41], v[18:33]
	v_mul_f32_e32 v34, v183, v219
	v_mul_f32_e32 v137, v34, v148
	s_waitcnt lgkmcnt(0)
	v_mfma_f32_32x32x16_bf16 v[2:17], v[42:45], v[38:41], v[2:17]
	s_cbranch_vccnz .LBB0_760
	v_cmp_gt_f32_e32 vcc, s51, v137
	s_cmp_eq_u64 vcc, exec
	s_cbranch_scc1 .LBB0_760
	s_sub_i32 s63, s16, 64
	s_cmp_gt_u32 s16, 63
	s_cselect_b64 s[40:41], -1, 0
	s_cmp_lt_u32 s16, 64
	s_cbranch_scc1 .Lsb_b_nopf
	v_add_u32_e32 v34, s63, v147
	v_ashrrev_i32_e32 v35, 31, v34
	v_lshlrev_b64 v[34:35], 13, v[34:35]
	v_lshl_add_u64 v[36:37], v[138:139], 0, v[34:35]
	v_lshl_add_u64 v[34:35], v[140:141], 0, v[34:35]
	global_load_dwordx4 v[50:53], v[36:37], off
	global_load_dwordx4 v[54:57], v[34:35], off
	v_add_u32_e32 v34, s63, v151
	v_ashrrev_i32_e32 v35, 31, v34
	v_lshlrev_b64 v[34:35], 13, v[34:35]
	v_lshl_add_u64 v[36:37], v[138:139], 0, v[34:35]
	v_lshl_add_u64 v[34:35], v[140:141], 0, v[34:35]
	global_load_dwordx4 v[58:61], v[36:37], off
	global_load_dwordx4 v[62:65], v[34:35], off
	v_add_u32_e32 v34, s63, v153
	v_ashrrev_i32_e32 v35, 31, v34
	v_lshlrev_b64 v[34:35], 13, v[34:35]
	v_lshl_add_u64 v[36:37], v[138:139], 0, v[34:35]
	v_lshl_add_u64 v[34:35], v[140:141], 0, v[34:35]
	global_load_dwordx4 v[66:69], v[36:37], off
	global_load_dwordx4 v[70:73], v[34:35], off
	v_add_u32_e32 v34, s63, v155
	v_ashrrev_i32_e32 v35, 31, v34
	v_lshlrev_b64 v[34:35], 13, v[34:35]
	v_lshl_add_u64 v[36:37], v[138:139], 0, v[34:35]
	v_lshl_add_u64 v[34:35], v[140:141], 0, v[34:35]
	global_load_dwordx4 v[86:89], v[36:37], off
	global_load_dwordx4 v[94:97], v[34:35], off
.LBB0_767:
	s_waitcnt vmcnt(15)
	ds_write_b128 v131, v[78:81] offset:4608
	s_waitcnt vmcnt(13)
	ds_write_b128 v131, v[90:93] offset:5760
	s_waitcnt vmcnt(11)
	ds_write_b128 v131, v[102:105] offset:6912
	s_waitcnt vmcnt(9)
	ds_write_b128 v131, v[114:117] offset:8064
	ds_read_b128 v[34:37], v133 offset:4608
	ds_read_b128 v[190:193], v133 offset:4640
	s_cmp_eq_u32 s62, s67
	s_cselect_b64 vcc, -1, 0
	v_cndmask_b32_e32 v143, 64, v1, vcc
	s_waitcnt lgkmcnt(1)
	v_mfma_f32_32x32x16_bf16 v[34:49], v[34:37], v[110:113], 0
	v_cmp_lt_u32_e32 vcc, v177, v143
	v_cmp_lt_u32_e64 s[4:5], v199, v143
	v_cmp_lt_u32_e64 s[6:7], v200, v143
	s_waitcnt lgkmcnt(0)
	v_mfma_f32_32x32x16_bf16 v[34:49], v[190:193], v[118:121], v[34:49]
	ds_read_b128 v[190:193], v133 offset:4672
	ds_read_b128 v[218:221], v133 offset:4704
	ds_write_b128 v131, v[74:77]
	ds_write_b128 v131, v[82:85] offset:1152
	ds_write_b128 v131, v[98:101] offset:2304
	s_waitcnt vmcnt(8)
	ds_write_b128 v131, v[106:109] offset:3456
	s_waitcnt lgkmcnt(5)
	v_mfma_f32_32x32x16_bf16 v[34:49], v[190:193], v[122:125], v[34:49]
	s_waitcnt lgkmcnt(4)
;     f32x16 c;
; #pragma unroll
;     for (int i = 0; i < 16; ++i) c[i] = c0;
; #pragma unroll
;     for (int s = 0; s < 4; ++s) c = __builtin_amdgcn_mfma_f32_32x32x16_bf16(kf[s], qf[s], c, 0, 0, 0);
;     return c;
; }
	v_mfma_f32_32x32x16_bf16 v[34:49], v[218:221], v[126:129], v[34:49]
	s_nop 11
	v_max_f32_e32 v34, v34, v34
	v_max_f32_e32 v35, v35, v35
	v_max_f32_e32 v36, v36, v36
	v_min_f32_e32 v34, 0x42fc0000, v34
	v_max_f32_e32 v37, v37, v37
	v_min_f32_e32 v35, 0x42fc0000, v35
	v_min_f32_e32 v36, 0x42fc0000, v36
	v_exp_f32_e32 v34, v34
	v_min_f32_e32 v37, 0x42fc0000, v37
	v_exp_f32_e32 v35, v35
	v_exp_f32_e32 v36, v36
	v_exp_f32_e32 v37, v37
	v_add_f32_e32 v144, 1.0, v34
	v_max_f32_e32 v38, v38, v38
	v_add_f32_e32 v145, 1.0, v35
	v_add_f32_e32 v148, 1.0, v36
	v_rcp_f32_e32 v144, v144
	v_min_f32_e32 v38, 0x42fc0000, v38
	v_add_f32_e32 v181, 1.0, v37
	v_rcp_f32_e32 v145, v145
	v_rcp_f32_e32 v148, v148
	v_exp_f32_e32 v38, v38
	v_rcp_f32_e32 v181, v181
	v_max_f32_e32 v39, v39, v39
	v_min_f32_e32 v39, 0x42fc0000, v39
	v_mul_f32_e32 v34, v34, v144
	v_exp_f32_e32 v39, v39
	v_cndmask_b32_e32 v183, 1.0, v144, vcc
	v_cndmask_b32_e64 v144, 1.0, v145, s[4:5]
	v_mul_f32_e32 v35, v35, v145
	v_cndmask_b32_e64 v145, 1.0, v148, s[6:7]
	v_mul_f32_e32 v36, v36, v148
	v_cndmask_b32_e32 v148, 0, v34, vcc
	v_cmp_lt_u32_e32 vcc, v201, v143
	v_cndmask_b32_e64 v34, 0, v35, s[4:5]
	v_mul_f32_e32 v35, v183, v144
	v_cndmask_b32_e32 v183, 1.0, v181, vcc
	v_mul_f32_e32 v37, v37, v181
	v_add_f32_e32 v181, 1.0, v38
	v_rcp_f32_e32 v181, v181
	v_max_f32_e32 v40, v40, v40
	v_add_f32_e32 v187, 1.0, v39
	v_min_f32_e32 v40, 0x42fc0000, v40
	v_rcp_f32_e32 v187, v187
	v_exp_f32_e32 v40, v40
	v_mul_f32_e32 v35, v145, v35
	v_cndmask_b32_e32 v37, 0, v37, vcc
	v_cmp_lt_u32_e32 vcc, v202, v143
	v_mul_f32_e32 v38, v38, v181
	v_mul_f32_e32 v185, v183, v35
	v_cndmask_b32_e32 v35, 1.0, v181, vcc
	v_cndmask_b32_e32 v38, 0, v38, vcc
	v_cmp_lt_u32_e32 vcc, v203, v143
	v_max_f32_e32 v41, v41, v41
	v_mul_f32_e32 v39, v39, v187
	v_cndmask_b32_e32 v181, 1.0, v187, vcc
	v_add_f32_e32 v187, 1.0, v40
	v_min_f32_e32 v41, 0x42fc0000, v41
	v_rcp_f32_e32 v187, v187
	v_exp_f32_e32 v41, v41
	v_cndmask_b32_e32 v39, 0, v39, vcc
	v_cmp_lt_u32_e32 vcc, v204, v143
	v_max_f32_e32 v42, v42, v42
	v_mul_f32_e32 v40, v40, v187
	v_cndmask_b32_e32 v189, 1.0, v187, vcc
	v_add_f32_e32 v187, 1.0, v41
	v_min_f32_e32 v42, 0x42fc0000, v42
	v_rcp_f32_e32 v187, v187
	v_exp_f32_e32 v42, v42
	v_cndmask_b32_e32 v40, 0, v40, vcc
	v_cmp_lt_u32_e32 vcc, v205, v143
	v_mul_f32_e32 v41, v41, v187
	v_max_f32_e32 v43, v43, v43
	v_cndmask_b32_e32 v190, 1.0, v187, vcc
	v_add_f32_e32 v187, 1.0, v42
	v_rcp_f32_e32 v187, v187
	v_min_f32_e32 v43, 0x42fc0000, v43
	v_exp_f32_e32 v43, v43
	v_cndmask_b32_e32 v41, 0, v41, vcc
	v_cmp_lt_u32_e32 vcc, v206, v143
	v_mul_f32_e32 v42, v42, v187
	v_max_f32_e32 v44, v44, v44
	v_cndmask_b32_e32 v191, 1.0, v187, vcc
	v_cndmask_b32_e32 v187, 0, v42, vcc
	v_add_f32_e32 v42, 1.0, v43
	v_min_f32_e32 v44, 0x42fc0000, v44
	v_rcp_f32_e32 v42, v42
	v_exp_f32_e32 v44, v44
	v_cmp_lt_u32_e32 vcc, v207, v143
	v_max_f32_e32 v45, v45, v45
	v_min_f32_e32 v45, 0x42fc0000, v45
	v_cndmask_b32_e32 v192, 1.0, v42, vcc
	v_mul_f32_e32 v42, v43, v42
	v_add_f32_e32 v43, 1.0, v44
	v_rcp_f32_e32 v43, v43
	v_exp_f32_e32 v45, v45
	v_cndmask_b32_e32 v193, 0, v42, vcc
	v_cmp_lt_u32_e32 vcc, v208, v143
	v_mul_f32_e32 v42, v191, v192
	v_max_f32_e32 v47, v47, v47
	v_cndmask_b32_e32 v191, 1.0, v43, vcc
	v_mul_f32_e32 v43, v44, v43
	v_max_f32_e32 v44, v46, v46
	v_cndmask_b32_e32 v194, 0, v43, vcc
	v_add_f32_e32 v43, 1.0, v45
	v_min_f32_e32 v44, 0x42fc0000, v44
	v_rcp_f32_e32 v43, v43
	v_exp_f32_e32 v44, v44
	v_min_f32_e32 v47, 0x42fc0000, v47
	v_exp_f32_e32 v47, v47
	v_cmp_lt_u32_e32 vcc, v209, v143
	v_max_f32_e32 v48, v48, v48
	v_min_f32_e32 v48, 0x42fc0000, v48
	v_cndmask_b32_e32 v46, 1.0, v43, vcc
	v_mul_f32_e32 v43, v45, v43
	v_add_f32_e32 v45, 1.0, v44
	v_rcp_f32_e32 v45, v45
	v_add_f32_e32 v218, 1.0, v47
	v_rcp_f32_e32 v218, v218
	v_exp_f32_e32 v48, v48
	v_cndmask_b32_e32 v43, 0, v43, vcc
	v_cmp_lt_u32_e32 vcc, v210, v143
	v_mul_f32_e32 v44, v44, v45
	v_max_f32_e32 v49, v49, v49
	v_cndmask_b32_e32 v195, 1.0, v45, vcc
	v_cndmask_b32_e32 v44, 0, v44, vcc
	v_cmp_lt_u32_e32 vcc, v211, v143
	v_mul_f32_e32 v47, v47, v218
	v_min_f32_e32 v49, 0x42fc0000, v49
	v_cndmask_b32_e32 v45, 1.0, v218, vcc
	v_add_f32_e32 v218, 1.0, v48
	v_rcp_f32_e32 v218, v218
	v_exp_f32_e32 v49, v49
	v_cndmask_b32_e32 v47, 0, v47, vcc
	v_cmp_lt_u32_e32 vcc, v212, v143
	v_mul_f32_e32 v48, v48, v218
	v_mul_f32_e32 v195, v195, v45
	v_cndmask_b32_e32 v219, 1.0, v218, vcc
	v_add_f32_e32 v218, 1.0, v49
	v_rcp_f32_e32 v218, v218
	v_cndmask_b32_e32 v48, 0, v48, vcc
	v_cmp_lt_u32_e32 vcc, v213, v143
	v_mul_f32_e32 v195, v219, v195
	v_mul_f32_e32 v49, v49, v218
	v_cndmask_b32_e32 v143, 1.0, v218, vcc
	v_mul_f32_e32 v195, v143, v195
	ds_bpermute_b32 v218, v135, v195
	v_mul_f32_e32 v42, v191, v42
	v_mul_f32_e32 v35, v35, v181
	v_mul_f32_e32 v42, v46, v42
	v_mul_f32_e32 v35, v189, v35
	s_waitcnt lgkmcnt(0)
; #define LAS __attribute__((address_space(3)))
; __device__ __forceinline__ unsigned cvtpk(float lo, float hi) { f32x2 v = {lo, hi}; bf2_t b = __builtin_convertvector(v, bf2_t); return __builtin_bit_cast(unsigned, b); }
; #define SB_LD(KF, VR, KK) do { _Pragma("unroll") for (int i = 0; i < 4; ++i) { const int id = lane + 64 * i; KF[i] = *(const bf16x8*)(kcol + (size_t)((KK) + (id >> 3)) * QKVW + (id & 7) * 8); VR[i] = *(const u32x4*)(vcol + (size_t)((KK) + (id >> 3)) * QKVW + (id & 7) * 8); } } while (0)
; __device__ __forceinline__ void pv32(f32x16 (&o)[2], LAS unsigned char* vl, const f32x16& p, int lane) {
;     bf16x8 pf[2];
; #pragma unroll
;     for (int s = 0; s < 2; ++s) { u32x4 w; w.x = cvtpk(p[8 * s], p[8 * s + 1]); w.y = cvtpk(p[8 * s + 2], p[8 * s + 3]); w.z = cvtpk(p[8 * s + 4], p[8 * s + 5]); w.w = cvtpk(p[8 * s + 6], p[8 * s + 7]); pf[s] = __builtin_bit_cast(bf16x8, w); }
;     const int i = lane & 15, gidx = lane >> 4, hh = gidx >> 1;
;     LAS unsigned char* base = vl + (4 * hh + (i >> 2)) * VL_PITCH + (16 * (gidx & 1) + 4 * (i & 3)) * 2;
; #pragma unroll
;     for (int s = 0; s < 2; ++s)
; #pragma unroll
;         for (int dh = 0; dh < 2; ++dh) {
;             const v4i16_t lo = __builtin_amdgcn_ds_read_tr16_b64_v4i16((LAS v4i16_t*)(base + (16 * s) * VL_PITCH + 64 * dh));
;             const v4i16_t hi = __builtin_amdgcn_ds_read_tr16_b64_v4i16((LAS v4i16_t*)(base + (16 * s + 8) * VL_PITCH + 64 * dh));
;             const bf16x8 vf = (bf16x8){lo[0], lo[1], lo[2], lo[3], hi[0], hi[1], hi[2], hi[3]};
;             o[dh] = __builtin_amdgcn_mfma_f32_32x32x16_bf16(vf, pf[s], o[dh], 0, 0, 0);
;         }
; }
; __device__ __forceinline__ void sb_item(bf16_t* qkv, LAS unsigned char* vl, int h, int qb, int lane, bool dry) {
;     ...
;     bf16x8 kfA[4], kfB[4]; u32x4 vrA[4], vrB[4];
;     int k0 = t0;
;     SB_LD(kfA, vrA, k0);
;     for (;;) {
;         const bool m1 = k0 - 32 >= 0; if (m1) SB_LD(kfB, vrB, k0 - 32);
;         SB_TILE(kfA, vrA, k0);
;         if (!m1 || __all(carry < 1e-38f)) break;
;         const bool m2 = k0 - 64 >= 0; if (m2) SB_LD(kfA, vrA, k0 - 64);
;         SB_TILE(kfB, vrB, k0 - 32);
;         if (!m2 || __all(carry < 1e-38f)) break;
;         k0 -= 64;
	v_cndmask_b32_e64 v223, 1.0, v218, s[2:3]
	ds_bpermute_b32 v222, v135, v42
	v_mul_f32_e32 v223, v137, v223
	v_mul_f32_e32 v35, v190, v35
	v_mul_f32_e32 v143, v143, v223
	ds_bpermute_b32 v221, v135, v35
	v_mul_f32_e32 v48, v48, v143
	v_mul_f32_e32 v143, v219, v143
	v_mul_f32_e32 v45, v45, v143
	v_mul_f32_e32 v47, v47, v143
	v_mul_f32_e32 v143, v44, v45
	v_mul_f32_e32 v44, v195, v218
	v_mul_f32_e32 v44, v137, v44
	s_waitcnt lgkmcnt(1)
	v_cndmask_b32_e64 v45, 1.0, v222, s[2:3]
	ds_bpermute_b32 v220, v135, v185
	v_mul_f32_e32 v137, v45, v44
	v_mul_f32_e32 v42, v42, v222
	v_mul_f32_e32 v195, v43, v137
	v_mul_f32_e32 v42, v42, v44
	s_waitcnt lgkmcnt(1)
	v_cndmask_b32_e64 v43, 1.0, v221, s[2:3]
	v_mul_f32_e32 v43, v43, v42
	v_mul_f32_e32 v41, v41, v43
	v_mul_f32_e32 v43, v190, v43
	v_mul_f32_e32 v44, v40, v43
	v_mul_f32_e32 v40, v189, v43
	v_mul_f32_e32 v35, v35, v221
	v_mul_f32_e32 v43, v39, v40
	v_mul_f32_e32 v39, v181, v40
	v_mul_f32_e32 v181, v35, v42
	s_waitcnt lgkmcnt(0)
	v_cndmask_b32_e64 v35, 1.0, v220, s[2:3]
	v_mul_f32_e32 v35, v35, v181
	v_mul_f32_e32 v40, v38, v39
	v_mul_f32_e32 v39, v37, v35
	v_mul_f32_e32 v35, v183, v35
	v_mul_f32_e32 v38, v145, v35
	v_cndmask_b32_e64 v36, 0, v36, s[6:7]
	v_mul_f32_e32 v45, v34, v38
	v_mul_f32_e32 v38, v144, v38
	v_mul_f32_e32 v42, v36, v35
	v_mul_f32_e32 v38, v148, v38
	ds_read_b64_tr_b16 v[34:35], v142
	ds_read_b64_tr_b16 v[36:37], v142 offset:1152
	v_cvt_pk_bf16_f32 v38, v38, v45
	v_cvt_pk_bf16_f32 v39, v42, v39
	v_cvt_pk_bf16_f32 v40, v40, v43
	v_cvt_pk_bf16_f32 v41, v44, v41
	ds_read_b64_tr_b16 v[44:45], v142 offset:1216
	ds_read_b64_tr_b16 v[42:43], v142 offset:64
	s_waitcnt lgkmcnt(2)
	v_mfma_f32_32x32x16_bf16 v[18:33], v[34:37], v[38:41], v[18:33]
	v_mul_f32_e32 v34, v46, v137
	v_mul_f32_e32 v46, v194, v34
	v_mul_f32_e32 v34, v191, v34
	v_mul_f32_e32 v137, v193, v34
	v_mul_f32_e32 v144, v192, v34
	ds_read_b64_tr_b16 v[34:35], v142 offset:2304
	ds_read_b64_tr_b16 v[36:37], v142 offset:3456
	v_cndmask_b32_e32 v49, 0, v49, vcc
	s_waitcnt lgkmcnt(2)
	v_mfma_f32_32x32x16_bf16 v[2:17], v[42:45], v[38:41], v[2:17]
	ds_read_b64_tr_b16 v[44:45], v142 offset:3520
	ds_read_b64_tr_b16 v[42:43], v142 offset:2368
	v_mul_f32_e32 v49, v49, v223
	v_mul_f32_e32 v38, v187, v144
	v_cvt_pk_bf16_f32 v38, v38, v137
	v_cvt_pk_bf16_f32 v39, v46, v195
	v_cvt_pk_bf16_f32 v40, v143, v47
	v_cvt_pk_bf16_f32 v41, v48, v49
	s_andn2_b64 vcc, exec, s[40:41]
	s_mov_b64 s[4:5], 0
	s_waitcnt lgkmcnt(2)
	v_mfma_f32_32x32x16_bf16 v[18:33], v[34:37], v[38:41], v[18:33]
	v_mul_f32_e32 v34, v185, v220
	v_mul_f32_e32 v137, v34, v181
	s_waitcnt lgkmcnt(0)
	v_mfma_f32_32x32x16_bf16 v[2:17], v[42:45], v[38:41], v[2:17]
	s_cbranch_vccnz .LBB0_760
	v_cmp_gt_f32_e32 vcc, s51, v137
	s_cmp_lg_u64 vcc, exec
	s_cselect_b64 s[4:5], -1, 0
	s_and_b64 s[6:7], s[4:5], exec
	s_cselect_b32 s16, s63, s16
	s_branch .LBB0_760
.Lsb_a_nopf:
	s_waitcnt vmcnt(0)
	s_branch .LBB0_763

; #define LAS __attribute__((address_space(3)))
; __device__ __forceinline__ unsigned cvtpk(float lo, float hi) { f32x2 v = {lo, hi}; bf2_t b = __builtin_convertvector(v, bf2_t); return __builtin_bit_cast(unsigned, b); }
; __device__ __forceinline__ void store_ot2(bf16_t* row0, size_t stride, const f32x16 (&o)[2], float sc, LAS unsigned char* kl, int lane) {
;     const int r = lane & 31, hh = lane >> 5;
; #pragma unroll
;     for (int dh = 0; dh < 2; ++dh)
; #pragma unroll
;         for (int g = 0; g < 4; ++g) { u32x2 w; w.x = cvtpk(o[dh][4 * g] * sc, o[dh][4 * g + 1] * sc); w.y = cvtpk(o[dh][4 * g + 2] * sc, o[dh][4 * g + 3] * sc);
;             *(LAS u32x2*)(kl + r * VL_PITCH + (32 * dh + 8 * g + 4 * hh) * 2) = w; }
; #pragma unroll
;     for (int i = 0; i < 4; ++i) { const int id = lane + 64 * i; const u32x4 v = *(const LAS u32x4*)(kl + (id >> 3) * VL_PITCH + (id & 7) * 16); *(u32x4*)(row0 + (size_t)(id >> 3) * stride + (id & 7) * 8) = v; }
; }
; __device__ __forceinline__ void sb_item(bf16_t* qkv, LAS unsigned char* vl, int h, int qb, int lane, bool dry) {
;     ...
;     if (!dry) store_ot2(q0, QKVW, o, 1.f, kl, lane);
.LBB0_772:
	s_waitcnt vmcnt(0)
	s_mov_b64 s[6:7], 0
	s_andn2_b64 vcc, exec, s[36:37]
	s_mov_b64 s[4:5], 0
	s_cbranch_vccnz .LBB0_774
	v_add_u32_e32 v34, v173, v214
	v_cvt_pk_bf16_f32 v18, v18, v19
	v_cvt_pk_bf16_f32 v19, v20, v21
	v_cvt_pk_bf16_f32 v20, v22, v23
	v_cvt_pk_bf16_f32 v21, v24, v25
	v_add_u32_e32 v22, 0x1000, v34
	v_cvt_pk_bf16_f32 v2, v2, v3
	v_cvt_pk_bf16_f32 v3, v4, v5
	v_cvt_pk_bf16_f32 v4, v6, v7
	v_cvt_pk_bf16_f32 v5, v8, v9
	ds_write2_b64 v22, v[18:19], v[20:21] offset0:64 offset1:66
	v_cvt_pk_bf16_f32 v18, v26, v27
	v_cvt_pk_bf16_f32 v19, v28, v29
	v_cvt_pk_bf16_f32 v20, v30, v31
	v_cvt_pk_bf16_f32 v21, v32, v33
	ds_write2_b64 v22, v[2:3], v[4:5] offset0:72 offset1:74
	v_cvt_pk_bf16_f32 v2, v10, v11
	v_cvt_pk_bf16_f32 v3, v12, v13
	ds_write2_b64 v22, v[18:19], v[20:21] offset0:68 offset1:70
	ds_write_b64 v34, v[2:3] offset:4704
	s_waitcnt vmcnt(7)
	v_cvt_pk_bf16_f32 v50, v14, v15
	s_mov_b64 s[4:5], -1

; #define LAS __attribute__((address_space(3)))
; #define MEM_LD(KF, VR, KK) do { _Pragma("unroll") for (int i = 0; i < 4; ++i) { const int id = lane + 64 * i; KF[i] = *(const bf16x8*)(kcol + (size_t)((KK) + (id >> 3)) * 512 + (id & 7) * 8); VR[i] = *(const u32x4*)(vcol + (size_t)((KK) + (id >> 3)) * 512 + (id & 7) * 8); } } while (0)
; #define MEM_TILE(KF, VR) do { bf16x8 kq_[4]; k_frag(kq_, kl, KF, lane); f32x16 s = qk32c(qf, kq_, negm); v_stage_store(vl, VR, lane); softmax_tile(s, 0xffffu, l); pv32(o, vl, s, lane); } while (0)
; __device__ __forceinline__ void k_frag(bf16x8 (&kq)[4], LAS unsigned char* kl, const bf16x8 (&kr)[4], int lane) {
; #pragma unroll
;     for (int i = 0; i < 4; ++i) { const int id = lane + 64 * i; *(LAS bf16x8*)(kl + (id >> 3) * VL_PITCH + (id & 7) * 16) = kr[i]; }
;     const int r = lane & 31, hh = lane >> 5;
; #pragma unroll
;     for (int s = 0; s < 4; ++s) kq[s] = *(const LAS bf16x8*)(kl + r * VL_PITCH + 32 * s + 16 * hh);
; }
; __device__ __forceinline__ void v_stage_store(LAS unsigned char* vl, const u32x4 (&vr)[4], int lane) {
; #pragma unroll
;     for (int i = 0; i < 4; ++i) { const int id = lane + 64 * i; *(LAS u32x4*)(vl + (id >> 3) * VL_PITCH + (id & 7) * 16) = vr[i]; }
; }
; __device__ __forceinline__ void softmax_tile(f32x16& s, unsigned mask, float& l) {
;     float ps = 0.f;
; #pragma unroll
;     for (int r = 0; r < 16; ++r) { const float p = ((mask >> r) & 1u) ? __builtin_amdgcn_exp2f(s[r]) : 0.f; s[r] = p; ps += p; }
;     l += ps;
; }
; __device__ __forceinline__ void mem_item(bf16_t* qkv, const bf16_t* KV, const float* mref_tab, LAS unsigned char* vl, int h, int qb, int lane, bool dry) {
;     ...
;     bf16x8 kfA[4], kfB[4]; u32x4 vrA[4], vrB[4];
;     MEM_LD(kfA, vrA, 0);
; #pragma unroll 1
;     for (int k0 = 0; k0 < MEML; k0 += 64) {
;         MEM_LD(kfB, vrB, k0 + 32);
;         MEM_TILE(kfA, vrA);
;         if (k0 + 64 < MEML) MEM_LD(kfA, vrA, k0 + 64);
;         MEM_TILE(kfB, vrB);
.LBB0_776:
	s_waitcnt vmcnt(15)
	ds_write_b128 v144, v[118:121] offset:4608
	s_waitcnt vmcnt(13)
	ds_write_b128 v144, v[130:133] offset:5760
	s_waitcnt vmcnt(11)
	ds_write_b128 v144, v[134:137] offset:6912
	s_waitcnt vmcnt(9)
	ds_write_b128 v144, v[50:53] offset:8064
	ds_read_b128 v[118:121], v145 offset:4608
	ds_read_b128 v[130:133], v145 offset:4640
	v_add_f32_e32 v50, 0, v191
	v_add_f32_e32 v50, v192, v50
	v_add_f32_e32 v50, v193, v50
	v_add_f32_e32 v50, v194, v50
	v_add_f32_e32 v134, v54, v50
	s_add_i32 s16, s16, 64
	v_lshl_add_u64 v[142:143], v[142:143], 0, s[26:27]
	s_waitcnt lgkmcnt(1)
	v_mfma_f32_32x32x16_bf16 v[50:65], v[118:121], v[66:69], v[2:17]
	v_add_f32_e32 v118, v183, v134
	v_add_f32_e32 v118, v185, v118
	v_add_f32_e32 v118, v187, v118
	v_add_f32_e32 v118, v189, v118
	v_add_f32_e32 v118, v190, v118
	v_add_f32_e32 v134, v221, v118
	ds_read_b128 v[118:121], v145 offset:4672
	s_waitcnt lgkmcnt(1)
	v_mfma_f32_32x32x16_bf16 v[50:65], v[130:133], v[70:73], v[50:65]
	v_add_f32_e32 v130, v195, v134
	v_add_f32_e32 v130, v218, v130
	v_add_f32_e32 v130, v219, v130
	v_add_f32_e32 v130, v220, v130
	v_add_f32_e32 v130, v222, v130
	v_add_f32_e32 v134, v148, v130
	ds_read_b128 v[130:133], v145 offset:4704
	s_waitcnt lgkmcnt(1)
	v_mfma_f32_32x32x16_bf16 v[50:65], v[118:121], v[74:77], v[50:65]
	ds_write_b128 v144, v[114:117]
	ds_write_b128 v144, v[122:125] offset:1152
	ds_write_b128 v144, v[126:129] offset:2304
	s_waitcnt vmcnt(8)
	ds_write_b128 v144, v[138:141] offset:3456
	ds_read_b64_tr_b16 v[114:115], v181
	ds_read_b64_tr_b16 v[116:117], v181 offset:1152
	s_and_b64 vcc, exec, s[6:7]
	s_waitcnt lgkmcnt(6)
	v_mfma_f32_32x32x16_bf16 v[50:65], v[130:133], v[78:81], v[50:65]
	s_nop 11
	v_exp_f32_e32 v50, v50
	v_exp_f32_e32 v51, v51
	v_exp_f32_e32 v52, v52
	v_exp_f32_e32 v53, v53
	v_exp_f32_e32 v54, v54
	v_exp_f32_e32 v118, v58
	v_add_f32_e32 v58, 0, v50
	v_exp_f32_e32 v55, v55
	v_add_f32_e32 v58, v51, v58
	v_exp_f32_e32 v56, v56
	v_add_f32_e32 v58, v52, v58
	v_exp_f32_e32 v57, v57
	v_add_f32_e32 v58, v53, v58
	v_add_f32_e32 v58, v54, v58
	v_add_f32_e32 v58, v55, v58
	v_add_f32_e32 v58, v56, v58
	v_add_f32_e32 v58, v57, v58
	v_cvt_pk_bf16_f32 v50, v50, v51
	v_cvt_pk_bf16_f32 v51, v52, v53
	v_cvt_pk_bf16_f32 v52, v54, v55
	v_cvt_pk_bf16_f32 v53, v56, v57
	ds_read_b64_tr_b16 v[56:57], v181 offset:1216
	ds_read_b64_tr_b16 v[54:55], v181 offset:64
	v_exp_f32_e32 v119, v59
	s_waitcnt lgkmcnt(2)
	v_mfma_f32_32x32x16_bf16 v[34:49], v[114:117], v[50:53], v[34:49]
	v_add_f32_e32 v58, v118, v58
	v_exp_f32_e32 v114, v60
	v_add_f32_e32 v120, v119, v58
	v_exp_f32_e32 v115, v61
	v_exp_f32_e32 v62, v62
	v_exp_f32_e32 v63, v63
	v_exp_f32_e32 v64, v64
	s_waitcnt lgkmcnt(0)
	v_mfma_f32_32x32x16_bf16 v[18:33], v[54:57], v[50:53], v[18:33]
	ds_read_b64_tr_b16 v[58:59], v181 offset:2304
	ds_read_b64_tr_b16 v[60:61], v181 offset:3456
	v_exp_f32_e32 v65, v65
	ds_read_b64_tr_b16 v[56:57], v181 offset:3520
	ds_read_b64_tr_b16 v[54:55], v181 offset:2368
	v_cvt_pk_bf16_f32 v50, v118, v119
	v_cvt_pk_bf16_f32 v51, v114, v115
	v_cvt_pk_bf16_f32 v52, v62, v63
	v_cvt_pk_bf16_f32 v53, v64, v65
	s_waitcnt lgkmcnt(2)
	s_nop 0
	v_mfma_f32_32x32x16_bf16 v[34:49], v[58:61], v[50:53], v[34:49]
	v_add_f32_e32 v58, v114, v120
	v_add_f32_e32 v58, v115, v58
	v_add_f32_e32 v58, v62, v58
	v_add_f32_e32 v58, v63, v58
	v_add_f32_e32 v58, v64, v58
	v_add_f32_e32 v58, v65, v58
	v_add_f32_e32 v148, v134, v58
	s_waitcnt lgkmcnt(0)
	v_mfma_f32_32x32x16_bf16 v[18:33], v[54:57], v[50:53], v[18:33]
	s_cbranch_vccnz .LBB0_779

; #define LAS __attribute__((address_space(3)))
; __device__ __forceinline__ void k_frag(bf16x8 (&kq)[4], LAS unsigned char* kl, const bf16x8 (&kr)[4], int lane) {
; #pragma unroll
;     for (int i = 0; i < 4; ++i) { const int id = lane + 64 * i; *(LAS bf16x8*)(kl + (id >> 3) * VL_PITCH + (id & 7) * 16) = kr[i]; }
;     const int r = lane & 31, hh = lane >> 5;
; #pragma unroll
;     for (int s = 0; s < 4; ++s) kq[s] = *(const LAS bf16x8*)(kl + r * VL_PITCH + 32 * s + 16 * hh);
; }
; __device__ __forceinline__ void v_stage_store(LAS unsigned char* vl, const u32x4 (&vr)[4], int lane) {
; #pragma unroll
;     for (int i = 0; i < 4; ++i) { const int id = lane + 64 * i; *(LAS u32x4*)(vl + (id >> 3) * VL_PITCH + (id & 7) * 16) = vr[i]; }
; }
.LBB0_785:
	s_waitcnt vmcnt(15)
	ds_write_b128 v148, v[66:69] offset:4608
	s_waitcnt vmcnt(13)
	ds_write_b128 v148, v[74:77] offset:5760
	s_waitcnt vmcnt(11)
	ds_write_b128 v148, v[82:85] offset:6912
	s_waitcnt vmcnt(9)
	ds_write_b128 v148, v[90:93] offset:8064
	ds_read_b128 v[236:239], v185 offset:4608
	ds_read_b128 v[240:243], v185 offset:4640
	v_sub_u32_e32 v219, v189, v219
	v_sub_u32_e32 v220, v189, v220
	v_cmp_gt_u32_e32 vcc, s57, v219
	s_waitcnt lgkmcnt(1)
	v_mfma_f32_32x32x16_bf16 v[50:65], v[236:239], v[114:117], v[2:17]
	ds_read_b128 v[236:239], v185 offset:4672
	v_sub_u32_e32 v221, v189, v221
	v_sub_u32_e32 v222, v189, v222
	v_sub_u32_e32 v224, v189, v224
	v_sub_u32_e32 v223, v189, v223
	v_sub_u32_e32 v233, v189, v233
	v_sub_u32_e32 v234, v189, v234
	s_waitcnt lgkmcnt(1)
	v_mfma_f32_32x32x16_bf16 v[50:65], v[240:243], v[118:121], v[50:65]
	ds_read_b128 v[240:243], v185 offset:4704
	ds_write_b128 v148, v[70:73]
	ds_write_b128 v148, v[78:81] offset:1152
	ds_write_b128 v148, v[86:89] offset:2304
	s_waitcnt vmcnt(8)
	ds_write_b128 v148, v[94:97] offset:3456
	s_waitcnt lgkmcnt(5)
	v_mfma_f32_32x32x16_bf16 v[50:65], v[236:239], v[122:125], v[50:65]
	s_waitcnt lgkmcnt(4)
	v_mfma_f32_32x32x16_bf16 v[50:65], v[240:243], v[126:129], v[50:65]
	s_nop 11
	v_exp_f32_e32 v50, v50
	v_exp_f32_e32 v51, v51
	v_exp_f32_e32 v52, v52
	v_exp_f32_e32 v53, v53
	v_exp_f32_e32 v54, v54
	v_cndmask_b32_e32 v219, 0, v50, vcc
	v_cmp_gt_u32_e32 vcc, s57, v220
	v_exp_f32_e32 v55, v55
	v_exp_f32_e32 v56, v56
	v_cndmask_b32_e32 v220, 0, v51, vcc
	v_cmp_gt_u32_e32 vcc, s57, v221
	v_exp_f32_e32 v57, v57
	v_add_f32_e32 v50, 0, v219
	v_cndmask_b32_e32 v221, 0, v52, vcc
	v_cmp_gt_u32_e32 vcc, s57, v222
	v_exp_f32_e32 v51, v58
	v_add_f32_e32 v50, v220, v50
	v_cndmask_b32_e32 v222, 0, v53, vcc
	v_cmp_gt_u32_e32 vcc, s57, v224
	v_add_f32_e32 v50, v221, v50
	v_sub_u32_e32 v52, v189, v225
	v_cndmask_b32_e32 v224, 0, v54, vcc
	v_cmp_gt_u32_e32 vcc, s57, v223
	v_add_f32_e32 v50, v222, v50
	v_add_f32_e32 v50, v224, v50
	v_cndmask_b32_e32 v223, 0, v55, vcc
	v_cmp_gt_u32_e32 vcc, s57, v233
	v_add_f32_e32 v50, v223, v50
	v_exp_f32_e32 v63, v63
	v_cndmask_b32_e32 v233, 0, v56, vcc
	v_cmp_gt_u32_e32 vcc, s57, v234
	v_add_f32_e32 v50, v233, v50
	v_cvt_pk_bf16_f32 v54, v219, v220
	v_cndmask_b32_e32 v57, 0, v57, vcc
	v_cmp_gt_u32_e32 vcc, s57, v52
	v_sub_u32_e32 v52, v189, v226
	v_add_f32_e32 v50, v57, v50
	v_cndmask_b32_e32 v225, 0, v51, vcc
	v_exp_f32_e32 v51, v59
	v_cmp_gt_u32_e32 vcc, s57, v52
	v_add_f32_e32 v50, v225, v50
	v_exp_f32_e32 v52, v62
	v_cndmask_b32_e32 v226, 0, v51, vcc
	v_exp_f32_e32 v51, v60
	v_add_f32_e32 v234, v226, v50
	v_sub_u32_e32 v50, v189, v227
	v_cmp_gt_u32_e32 vcc, s57, v50
	v_exp_f32_e32 v50, v61
	v_cvt_pk_bf16_f32 v55, v221, v222
	v_cndmask_b32_e32 v227, 0, v51, vcc
	v_sub_u32_e32 v51, v189, v228
	v_cmp_gt_u32_e32 vcc, s57, v51
	v_cvt_pk_bf16_f32 v56, v224, v223
	v_cvt_pk_bf16_f32 v57, v233, v57
	v_cndmask_b32_e32 v62, 0, v50, vcc
	v_sub_u32_e32 v50, v189, v229
	v_cmp_gt_u32_e32 vcc, s57, v50
	v_sub_u32_e32 v229, v189, v230
	v_exp_f32_e32 v64, v64
	v_cndmask_b32_e32 v228, 0, v52, vcc
	ds_read_b64_tr_b16 v[50:51], v218
	ds_read_b64_tr_b16 v[52:53], v218 offset:1152
	ds_read_b64_tr_b16 v[60:61], v218 offset:1216
	ds_read_b64_tr_b16 v[58:59], v218 offset:64
	s_waitcnt lgkmcnt(2)
	v_mfma_f32_32x32x16_bf16 v[34:49], v[50:53], v[54:57], v[34:49]
	v_cmp_gt_u32_e32 vcc, s57, v229
	v_sub_u32_e32 v50, v189, v231
	v_exp_f32_e32 v65, v65
	v_cndmask_b32_e32 v63, 0, v63, vcc
	v_cmp_gt_u32_e32 vcc, s57, v50
	ds_read_b64_tr_b16 v[50:51], v218 offset:2304
	ds_read_b64_tr_b16 v[52:53], v218 offset:3456
	v_sub_u32_e32 v219, v189, v232
	s_waitcnt lgkmcnt(2)
	v_mfma_f32_32x32x16_bf16 v[18:33], v[58:61], v[54:57], v[18:33]
	ds_read_b64_tr_b16 v[60:61], v218 offset:3520
	ds_read_b64_tr_b16 v[58:59], v218 offset:2368
	v_cndmask_b32_e32 v64, 0, v64, vcc
	v_cmp_gt_u32_e32 vcc, s57, v219
	v_cvt_pk_bf16_f32 v54, v225, v226
	v_cvt_pk_bf16_f32 v55, v227, v62
	v_cndmask_b32_e32 v65, 0, v65, vcc
	v_cvt_pk_bf16_f32 v56, v228, v63
	v_cvt_pk_bf16_f32 v57, v64, v65
	s_waitcnt lgkmcnt(2)
	s_nop 0
	v_mfma_f32_32x32x16_bf16 v[34:49], v[50:53], v[54:57], v[34:49]
	v_add_f32_e32 v50, v227, v234
	v_add_f32_e32 v50, v62, v50
	v_add_f32_e32 v50, v228, v50
	v_add_f32_e32 v50, v63, v50
	v_add_f32_e32 v50, v64, v50
	v_add_f32_e32 v50, v65, v50
	v_add_f32_e32 v181, v181, v50
	s_waitcnt lgkmcnt(0)
	v_mfma_f32_32x32x16_bf16 v[18:33], v[58:61], v[54:57], v[18:33]
	s_xor_b64 s[38:39], s[38:39], -1
	s_andn2_b64 vcc, exec, s[38:39]
	s_cbranch_vccz .LBB0_783

; #define DSA_LD(KF, VR, KK) do { _Pragma("unroll") for (int i = 0; i < 4; ++i) { const int id = lane + 64 * i; KF[i] = *(const bf16x8*)(kcol + (size_t)(cm + (((KK) + (id >> 3)) << sh)) * QKVW + (id & 7) * 8); VR[i] = *(const u32x4*)(vcol + (size_t)(cm + (((KK) + (id >> 3)) << sh)) * QKVW + (id & 7) * 8); } } while (0)
; __device__ __forceinline__ void dsa_item(bf16_t* qkv, const float* mref_tab, LAS unsigned char* vl, int hs, int c, int i0, int lane, bool dry) {
;     ...
;         bf16x8 kfA[4], kfB[4]; u32x4 vrA[4], vrB[4];
;         int k0 = ks;
;         DSA_LD(kfA, vrA, k0);
;         for (;;) {
;             const bool m1 = k0 + 32 <= qmax; if (m1) DSA_LD(kfB, vrB, k0 + 32);
;             DSA_TILE(kfA, vrA, k0);
;             if (!m1) break;
;             const bool m2 = k0 + 64 <= qmax; if (m2) DSA_LD(kfA, vrA, k0 + 64);
;             DSA_TILE(kfB, vrB, k0 + 32);
;             if (!m2) break;
;             k0 += 64;
;         }
.LBB0_788:
	s_waitcnt vmcnt(15)
	ds_write_b128 v148, v[98:101] offset:4608
	s_waitcnt vmcnt(13)
	ds_write_b128 v148, v[106:109] offset:5760
	s_waitcnt vmcnt(11)
	ds_write_b128 v148, v[130:133] offset:6912
	s_waitcnt vmcnt(9)
	ds_write_b128 v148, v[138:141] offset:8064
	ds_read_b128 v[218:221], v185 offset:4608
	ds_read_b128 v[222:225], v185 offset:4640
	ds_read_b128 v[226:229], v185 offset:4672
	ds_read_b128 v[230:233], v185 offset:4704
	ds_write_b128 v148, v[102:105]
	ds_write_b128 v148, v[110:113] offset:1152
	ds_write_b128 v148, v[134:137] offset:2304
	s_waitcnt vmcnt(8)
	ds_write_b128 v148, v[142:145] offset:3456
	s_waitcnt lgkmcnt(7)
	v_mfma_f32_32x32x16_bf16 v[50:65], v[218:221], v[114:117], v[2:17]
	v_add_u32_e32 v219, s65, v177
	v_sub_u32_e32 v218, v187, v219
	v_add_u32_e32 v220, 1, v219
	v_add_u32_e32 v221, 2, v219
	v_cmp_gt_u32_e32 vcc, s57, v218
	v_add_u32_e32 v234, 11, v219
	v_add_u32_e32 v218, v196, v197
	s_waitcnt lgkmcnt(6)
	v_mfma_f32_32x32x16_bf16 v[50:65], v[222:225], v[118:121], v[50:65]
	v_sub_u32_e32 v225, v187, v220
	v_add_u32_e32 v222, 3, v219
	v_add_u32_e32 v224, 8, v219
	v_add_u32_e32 v223, 9, v219
	s_waitcnt lgkmcnt(5)
	v_mfma_f32_32x32x16_bf16 v[50:65], v[226:229], v[122:125], v[50:65]
	v_sub_u32_e32 v226, v187, v221
	v_sub_u32_e32 v227, v187, v222
	v_sub_u32_e32 v228, v187, v224
	v_sub_u32_e32 v229, v187, v223
	s_waitcnt lgkmcnt(4)
	v_mfma_f32_32x32x16_bf16 v[50:65], v[230:233], v[126:129], v[50:65]
	v_add_u32_e32 v233, 10, v219
	v_add_u32_e32 v230, 25, v219
	s_nop 9
	v_exp_f32_e32 v50, v50
	v_exp_f32_e32 v51, v51
	v_exp_f32_e32 v52, v52
	v_exp_f32_e32 v53, v53
	v_exp_f32_e32 v54, v54
	v_cndmask_b32_e32 v231, 0, v50, vcc
	v_cmp_gt_u32_e32 vcc, s57, v225
	v_exp_f32_e32 v55, v55
	v_exp_f32_e32 v56, v56
	v_cndmask_b32_e32 v232, 0, v51, vcc
	v_cmp_gt_u32_e32 vcc, s57, v226
	v_sub_u32_e32 v51, v187, v233
	v_add_u32_e32 v225, 16, v219
	v_cndmask_b32_e32 v235, 0, v52, vcc
	v_cmp_gt_u32_e32 vcc, s57, v227
	v_sub_u32_e32 v52, v187, v234
	v_add_u32_e32 v226, 17, v219
	v_cndmask_b32_e32 v236, 0, v53, vcc
	v_cmp_gt_u32_e32 vcc, s57, v228
	v_add_f32_e32 v50, 0, v231
	v_add_u32_e32 v227, 18, v219
	v_cndmask_b32_e32 v237, 0, v54, vcc
	v_cmp_gt_u32_e32 vcc, s57, v229
	v_add_f32_e32 v50, v232, v50
	v_add_f32_e32 v50, v235, v50
	v_cndmask_b32_e32 v238, 0, v55, vcc
	v_cmp_gt_u32_e32 vcc, s57, v51
	v_exp_f32_e32 v51, v57
	v_add_f32_e32 v50, v236, v50
	v_cndmask_b32_e32 v239, 0, v56, vcc
	v_cmp_gt_u32_e32 vcc, s57, v52
	v_sub_u32_e32 v52, v187, v225
	v_add_f32_e32 v50, v237, v50
	v_cndmask_b32_e32 v57, 0, v51, vcc
	v_exp_f32_e32 v51, v58
	v_cmp_gt_u32_e32 vcc, s57, v52
	v_sub_u32_e32 v52, v187, v226
	v_add_u32_e32 v228, 19, v219
	v_cndmask_b32_e32 v240, 0, v51, vcc
	v_exp_f32_e32 v51, v59
	v_cmp_gt_u32_e32 vcc, s57, v52
	v_sub_u32_e32 v52, v187, v227
	v_add_f32_e32 v50, v238, v50
	v_cndmask_b32_e32 v241, 0, v51, vcc
	v_exp_f32_e32 v51, v60
	v_cmp_gt_u32_e32 vcc, s57, v52
	v_sub_u32_e32 v52, v187, v228
	v_add_f32_e32 v50, v239, v50
	v_cndmask_b32_e32 v242, 0, v51, vcc
	v_exp_f32_e32 v51, v61
	v_cmp_gt_u32_e32 vcc, s57, v52
	v_add_f32_e32 v50, v57, v50
	v_add_f32_e32 v50, v240, v50
	v_cndmask_b32_e32 v243, 0, v51, vcc
	v_exp_f32_e32 v51, v62
	v_add_u32_e32 v229, 24, v219
	v_add_f32_e32 v50, v241, v50
	v_sub_u32_e32 v52, v187, v229
	v_add_f32_e32 v50, v242, v50
	v_cmp_gt_u32_e32 vcc, s57, v52
	v_add_f32_e32 v50, v243, v50
	v_exp_f32_e32 v55, v63
	v_cndmask_b32_e32 v62, 0, v51, vcc
	v_add_f32_e32 v244, v62, v50
	ds_read_b64_tr_b16 v[50:51], v218
	ds_read_b64_tr_b16 v[52:53], v218 offset:1152
	ds_read_b64_tr_b16 v[60:61], v218 offset:1216
	ds_read_b64_tr_b16 v[58:59], v218 offset:64
	v_sub_u32_e32 v54, v187, v230
	v_cmp_gt_u32_e32 vcc, s57, v54
	v_cvt_pk_bf16_f32 v54, v231, v232
	v_cvt_pk_bf16_f32 v56, v237, v238
	v_cndmask_b32_e32 v63, 0, v55, vcc
	v_cvt_pk_bf16_f32 v55, v235, v236
	v_cvt_pk_bf16_f32 v57, v239, v57
	v_exp_f32_e32 v64, v64
	v_add_u32_e32 v231, 26, v219
	s_waitcnt lgkmcnt(2)
	v_mfma_f32_32x32x16_bf16 v[34:49], v[50:53], v[54:57], v[34:49]
	v_sub_u32_e32 v50, v187, v231
	v_exp_f32_e32 v65, v65
	v_cmp_gt_u32_e32 vcc, s57, v50
	v_add_u32_e32 v232, 27, v219
	ds_read_b64_tr_b16 v[50:51], v218 offset:2304
	ds_read_b64_tr_b16 v[52:53], v218 offset:3456
	v_sub_u32_e32 v235, v187, v232
	v_cndmask_b32_e32 v64, 0, v64, vcc
	s_waitcnt lgkmcnt(2)
	v_mfma_f32_32x32x16_bf16 v[18:33], v[58:61], v[54:57], v[18:33]
	ds_read_b64_tr_b16 v[60:61], v218 offset:3520
	ds_read_b64_tr_b16 v[58:59], v218 offset:2368
	v_cmp_gt_u32_e32 vcc, s57, v235
	v_cvt_pk_bf16_f32 v54, v240, v241
	v_cvt_pk_bf16_f32 v55, v242, v243
	v_cndmask_b32_e32 v65, 0, v65, vcc
	v_cvt_pk_bf16_f32 v56, v62, v63
	v_cvt_pk_bf16_f32 v57, v64, v65
	s_andn2_b64 vcc, exec, s[38:39]
	s_waitcnt lgkmcnt(2)
	v_mfma_f32_32x32x16_bf16 v[34:49], v[50:53], v[54:57], v[34:49]
	v_add_f32_e32 v50, v63, v244
	v_add_f32_e32 v50, v64, v50
	v_add_f32_e32 v50, v65, v50
	v_add_f32_e32 v181, v181, v50
	s_waitcnt lgkmcnt(0)
	v_mfma_f32_32x32x16_bf16 v[18:33], v[58:61], v[54:57], v[18:33]
	s_cbranch_vccnz .LBB0_791
	s_add_i32 s67, s65, 64
	s_cmp_le_i32 s67, s66
	s_cselect_b64 s[38:39], -1, 0
	s_cmp_gt_i32 s67, s66
	s_cbranch_scc1 .Ldsa_b_nopf
	v_add_u32_e32 v50, s67, v147
	v_lshlrev_b32_e32 v50, s63, v50
	v_add_u32_e32 v50, s64, v50
	v_ashrrev_i32_e32 v51, 31, v50
	v_lshlrev_b64 v[50:51], 13, v[50:51]
	v_lshl_add_u64 v[52:53], v[192:193], 0, v[50:51]
	v_lshl_add_u64 v[50:51], v[194:195], 0, v[50:51]
	global_load_dwordx4 v[98:101], v[52:53], off
	global_load_dwordx4 v[102:105], v[50:51], off
	v_add_u32_e32 v50, s67, v151
	v_lshlrev_b32_e32 v50, s63, v50
	v_add_u32_e32 v50, s64, v50
	v_ashrrev_i32_e32 v51, 31, v50
	v_lshlrev_b64 v[50:51], 13, v[50:51]
	v_lshl_add_u64 v[52:53], v[192:193], 0, v[50:51]
	v_lshl_add_u64 v[50:51], v[194:195], 0, v[50:51]
	global_load_dwordx4 v[106:109], v[52:53], off
	global_load_dwordx4 v[110:113], v[50:51], off
	v_add_u32_e32 v50, s67, v153
	v_lshlrev_b32_e32 v50, s63, v50
	v_add_u32_e32 v50, s64, v50
	v_ashrrev_i32_e32 v51, 31, v50
	v_lshlrev_b64 v[50:51], 13, v[50:51]
	v_lshl_add_u64 v[52:53], v[192:193], 0, v[50:51]
	v_lshl_add_u64 v[50:51], v[194:195], 0, v[50:51]
	global_load_dwordx4 v[130:133], v[52:53], off
	global_load_dwordx4 v[134:137], v[50:51], off
	v_add_u32_e32 v50, s67, v155
	v_lshlrev_b32_e32 v50, s63, v50
	v_add_u32_e32 v50, s64, v50
	v_ashrrev_i32_e32 v51, 31, v50
	v_lshlrev_b64 v[50:51], 13, v[50:51]
	v_lshl_add_u64 v[52:53], v[192:193], 0, v[50:51]
	v_lshl_add_u64 v[50:51], v[194:195], 0, v[50:51]
	global_load_dwordx4 v[138:141], v[52:53], off
	global_load_dwordx4 v[142:145], v[50:51], off
	s_mov_b32 s65, s67
	s_branch .LBB0_785
